# v48 plus act_fix_phase de-serialised: the item's 14 f32x4 loads issued up front (one wait) instead of six load/wait/fma groups, same fma order
# speedup vs baseline: 1.0078x; 1.0028x over previous
; __device__ __forceinline__ unsigned cvt_pk_bf16(float lo, float hi) { const f32x2 v = {lo, hi}; unsigned r = __builtin_bit_cast(unsigned, __builtin_convertvector(v, bf16x2_t)); asm volatile("" : "+v"(r)); return r; }
; __device__ __forceinline__ float silu_f(float x) { return x * __builtin_amdgcn_rcpf(1.0f + __expf(-x)); }
; __device__ __forceinline__ void act_fix_phase(const Frame& F, KArgs* A_, int layer) {
;     ...
;     for (size_t it = gt; it < (size_t)NT * 2 * CG; it += NGT) {
;         const int pm = (int)(it / (2 * CG)), rem = (int)(it % (2 * CG)), i = rem / CG, col = (rem % CG) * 4;
;         if ((pm & 7) == 0) continue;
;         const float* H = halo + (size_t)pm * 4 * DFF2; const float* Hp = H - (size_t)4 * DFF2;
;         const float* h0p = H + (size_t)i * DFF2; const float* h1p = i == 0 ? Hp + (size_t)3 * DFF2 : H; const float* h2p = i == 0 ? Hp + (size_t)2 * DFF2 : Hp + (size_t)3 * DFF2;
;         f32x4 c[2];
; #pragma unroll
;         for (int s = 0; s < 2; ++s) { const int cc = s * DFF + col;
;             c[s] = *(const f32x4*)(cbias + cc) + *(const f32x4*)(cw + cc) * *(const f32x4*)(h2p + cc) + *(const f32x4*)(cw + DFF2 + cc) * *(const f32x4*)(h1p + cc) + *(const f32x4*)(cw + 2 * DFF2 + cc) * *(const f32x4*)(h0p + cc); }
;         u32x2 pk; pk.x = cvt_pk_bf16(silu_f(c[0][0]) * c[1][0], silu_f(c[0][1]) * c[1][1]); pk.y = cvt_pk_bf16(silu_f(c[0][2]) * c[1][2], silu_f(c[0][3]) * c[1][3]);
;         *(u32x2*)(act + (size_t)(pm * 256 + i) * DFF + col) = pk;
;     }
.LBB0_2097:
	s_mov_b32 s2, 0xba2e8ba3
	v_mul_hi_u32 v0, v2, s2
	v_bfe_u32 v4, v0, 11, 3
	v_cmp_ne_u32_e32 vcc, 0, v4
	s_and_saveexec_b64 s[24:25], vcc
	s_cbranch_execz .LBB0_2096
	v_lshrrev_b32_e32 v30, 11, v0
	v_mul_u32_u24_e32 v0, 0xb00, v30
	v_sub_u32_e32 v0, v2, v0
	s_movk_i32 s2, 0x580
	v_cmp_gt_u32_e32 vcc, s2, v0
	s_movk_i32 s2, 0x57f
	v_lshlrev_b32_e32 v4, 2, v0
	v_cmp_lt_u32_e64 s[6:7], s2, v0
	v_mul_u32_u24_e32 v0, 0x2c000, v30
	s_mov_b32 s2, 0xffff5000
	v_lshl_add_u64 v[6:7], s[10:11], 0, v[0:1]
	s_mov_b32 s3, -1
	v_mov_b32_e32 v0, 0xb000
	v_lshl_add_u64 v[8:9], v[6:7], 0, s[2:3]
	s_mov_b32 s2, 0xfffea000
	v_add_u32_e32 v5, 0xffffea00, v4
	v_cndmask_b32_e64 v0, 0, v0, s[6:7]
	s_mov_b32 s3, -1
	v_cndmask_b32_e32 v4, v5, v4, vcc
	v_lshl_add_u64 v[18:19], v[6:7], 0, v[0:1]
	v_cndmask_b32_e32 v21, v7, v9, vcc
	v_cndmask_b32_e32 v20, v6, v8, vcc
	v_lshl_add_u64 v[6:7], v[6:7], 0, s[2:3]
	v_mov_b32_e32 v5, v1
	v_cndmask_b32_e32 v23, v9, v7, vcc
	v_cndmask_b32_e32 v22, v8, v6, vcc
	v_lshlrev_b64 v[24:25], 2, v[4:5]
	v_add_u32_e32 v0, 0x1600, v4
	v_lshlrev_b64 v[28:29], 2, v[0:1]
	v_lshl_add_u64 v[6:7], s[16:17], 0, v[24:25]
	global_load_dwordx4 v[32:35], v[6:7], off
	v_lshl_add_u64 v[8:9], s[14:15], 0, v[24:25]
	global_load_dwordx4 v[36:39], v[8:9], off
	v_lshl_add_u64 v[10:11], v[22:23], 0, v[24:25]
	global_load_dwordx4 v[40:43], v[10:11], off
	v_lshl_add_u64 v[12:13], s[18:19], 0, v[24:25]
	global_load_dwordx4 v[44:47], v[12:13], off
	v_lshl_add_u64 v[6:7], v[20:21], 0, v[24:25]
	global_load_dwordx4 v[48:51], v[6:7], off
	v_lshl_add_u64 v[8:9], s[20:21], 0, v[24:25]
	global_load_dwordx4 v[52:55], v[8:9], off
	v_lshl_add_u64 v[10:11], v[18:19], 0, v[24:25]
	global_load_dwordx4 v[56:59], v[10:11], off
	v_lshl_add_u64 v[12:13], s[16:17], 0, v[28:29]
	global_load_dwordx4 v[60:63], v[12:13], off
	v_lshl_add_u64 v[6:7], s[14:15], 0, v[28:29]
	global_load_dwordx4 v[64:67], v[6:7], off
	v_lshl_add_u64 v[8:9], v[22:23], 0, v[28:29]
	global_load_dwordx4 v[68:71], v[8:9], off
	v_lshl_add_u64 v[10:11], s[18:19], 0, v[28:29]
	global_load_dwordx4 v[72:75], v[10:11], off
	v_lshl_add_u64 v[12:13], v[20:21], 0, v[28:29]
	global_load_dwordx4 v[76:79], v[12:13], off
	v_lshl_add_u64 v[6:7], s[20:21], 0, v[28:29]
	global_load_dwordx4 v[80:83], v[6:7], off
	v_lshl_add_u64 v[8:9], v[18:19], 0, v[28:29]
	global_load_dwordx4 v[84:87], v[8:9], off
	s_waitcnt vmcnt(0)
	v_cndmask_b32_e64 v31, 0, 1, s[6:7]
	s_movk_i32 s2, 0x1600
	v_pk_fma_f32 v[14:15], v[36:37], v[40:41], v[32:33]
	v_pk_fma_f32 v[16:17], v[38:39], v[42:43], v[34:35]
	v_pk_fma_f32 v[14:15], v[44:45], v[48:49], v[14:15]
	v_pk_fma_f32 v[16:17], v[46:47], v[50:51], v[16:17]
	v_pk_fma_f32 v[26:27], v[52:53], v[56:57], v[14:15]
	v_pk_fma_f32 v[24:25], v[54:55], v[58:59], v[16:17]
	v_pk_fma_f32 v[14:15], v[64:65], v[68:69], v[60:61]
	v_pk_fma_f32 v[16:17], v[66:67], v[70:71], v[62:63]
	v_pk_fma_f32 v[14:15], v[72:73], v[76:77], v[14:15]
	v_pk_fma_f32 v[16:17], v[74:75], v[78:79], v[16:17]
	v_pk_fma_f32 v[6:7], v[80:81], v[84:85], v[14:15]
	v_pk_fma_f32 v[8:9], v[82:83], v[86:87], v[16:17]
	v_mul_f32_e32 v0, 0xbfb8aa3b, v26
	v_exp_f32_e32 v0, v0
	s_nop 0
	v_add_f32_e32 v0, 1.0, v0
	v_rcp_f32_e32 v10, v0
	v_mul_f32_e32 v0, 0xbfb8aa3b, v27
	v_exp_f32_e32 v0, v0
	s_nop 0
	v_add_f32_e32 v0, 1.0, v0
	v_rcp_f32_e32 v11, v0
	v_mul_f32_e32 v0, 0xbfb8aa3b, v24
	v_exp_f32_e32 v0, v0
	v_pk_mul_f32 v[10:11], v[26:27], v[10:11]
	s_nop 0
	v_pk_mul_f32 v[6:7], v[10:11], v[6:7]
	v_add_f32_e32 v0, 1.0, v0
	v_rcp_f32_e32 v10, v0
	v_mul_f32_e32 v0, 0xbfb8aa3b, v25
	v_exp_f32_e32 v0, v0
	v_cvt_pk_bf16_f32 v6, v6, v7
	v_add_f32_e32 v0, 1.0, v0
	v_rcp_f32_e32 v11, v0
	v_lshl_or_b32 v0, v30, 8, v31
	v_mul_lo_u32 v0, v0, s2
	v_pk_mul_f32 v[10:11], v[24:25], v[10:11]
	s_nop 0
	v_pk_mul_f32 v[8:9], v[10:11], v[8:9]
	s_nop 0
	v_cvt_pk_bf16_f32 v7, v8, v9
	v_lshl_add_u64 v[8:9], v[0:1], 1, s[12:13]
	v_lshl_add_u64 v[4:5], v[4:5], 1, v[8:9]
	global_store_dwordx2 v[4:5], v[6:7], off
	s_branch .LBB0_2096
